# forget-logit phase: all 32 operand loads of the 16-MFMA chain issued up front with counted waits (was 2-3 in flight)
# speedup vs baseline: 1.0103x; 1.0036x over previous
.LBB0_643:
	v_readlane_b32 s2, v254, 32
	v_readlane_b32 s3, v254, 33
	s_and_b64 s[2:3], s[38:39], s[2:3]
	s_mov_b64 s[4:5], 0
	s_andn2_b64 vcc, exec, s[2:3]
	s_mov_b64 s[2:3], 0
	v_readlane_b32 s6, v254, 55
	v_readlane_b32 s7, v254, 56
	s_cbranch_vccnz .LBB0_645
	s_ashr_i32 s7, s6, 31
	s_lshl_b64 s[2:3], s[6:7], 18
	v_readlane_b32 s6, v254, 47
	s_add_u32 s6, s6, s2
	v_readlane_b32 s2, v254, 46
	v_mov_b32_e32 v40, v247
	s_waitcnt vmcnt(0)
	s_barrier
	s_addc_u32 s7, s2, s3
	s_load_dwordx2 s[2:3], s[88:89], 0x88
	v_mov_b32_e32 v3, v209
	v_readfirstlane_b32 s8, v40
	s_ashr_i32 s8, s8, 6
	s_lshl_b32 s10, s8, 8
	s_ashr_i32 s11, s10, 31
	v_and_b32_e32 v41, 31, v40
	s_lshl_b64 s[10:11], s[10:11], 1
	v_bfe_u32 v42, v40, 5, 1
	s_add_u32 s12, s82, s10
	v_lshlrev_b32_e32 v2, 12, v41
	s_addc_u32 s13, s83, s11
	v_lshlrev_b32_e32 v208, 4, v42
	v_lshl_add_u64 v[2:3], s[82:83], 0, v[2:3]
	v_lshl_add_u64 v[0:1], s[12:13], 0, v[208:209]
	v_lshl_add_u64 v[2:3], v[2:3], 0, s[10:11]
	v_readlane_b32 s12, v253, 59
	v_lshl_add_u64 v[8:9], v[2:3], 0, v[208:209]
	s_mov_b32 s9, 0x8800000
	v_or_b32_e32 v2, s12, v41
	v_ashrrev_i32_e32 v3, 31, v2
	v_lshlrev_b64 v[2:3], 12, v[2:3]
	v_lshl_add_u64 v[10:11], v[0:1], 0, v[2:3]
	v_add_co_u32_e32 v0, vcc, s9, v10
	s_mov_b32 s9, 0x8320000
	s_nop 0
	v_addc_co_u32_e32 v1, vcc, 0, v11, vcc
	s_mov_b64 s[10:11], 0x8800000
	v_lshl_add_u64 v[36:37], v[10:11], 0, s[10:11]
	s_mov_b64 s[10:11], 0x8320000
	v_lshl_add_u64 v[38:39], v[8:9], 0, s[10:11]
	global_load_dwordx4 v[48:51], v[36:37], off
	global_load_dwordx4 v[112:115], v[38:39], off
	global_load_dwordx4 v[52:55], v[36:37], off offset:32
	global_load_dwordx4 v[116:119], v[38:39], off offset:32
	global_load_dwordx4 v[56:59], v[36:37], off offset:64
	global_load_dwordx4 v[120:123], v[38:39], off offset:64
	global_load_dwordx4 v[60:63], v[36:37], off offset:96
	global_load_dwordx4 v[124:127], v[38:39], off offset:96
	global_load_dwordx4 v[64:67], v[36:37], off offset:128
	global_load_dwordx4 v[128:131], v[38:39], off offset:128
	global_load_dwordx4 v[68:71], v[36:37], off offset:160
	global_load_dwordx4 v[132:135], v[38:39], off offset:160
	global_load_dwordx4 v[72:75], v[36:37], off offset:192
	global_load_dwordx4 v[136:139], v[38:39], off offset:192
	global_load_dwordx4 v[76:79], v[36:37], off offset:224
	global_load_dwordx4 v[140:143], v[38:39], off offset:224
	global_load_dwordx4 v[80:83], v[36:37], off offset:256
	global_load_dwordx4 v[144:147], v[38:39], off offset:256
	global_load_dwordx4 v[84:87], v[36:37], off offset:288
	global_load_dwordx4 v[148:151], v[38:39], off offset:288
	global_load_dwordx4 v[88:91], v[36:37], off offset:320
	global_load_dwordx4 v[152:155], v[38:39], off offset:320
	global_load_dwordx4 v[92:95], v[36:37], off offset:352
	global_load_dwordx4 v[156:159], v[38:39], off offset:352
	global_load_dwordx4 v[96:99], v[36:37], off offset:384
	global_load_dwordx4 v[160:163], v[38:39], off offset:384
	global_load_dwordx4 v[100:103], v[36:37], off offset:416
	global_load_dwordx4 v[164:167], v[38:39], off offset:416
	global_load_dwordx4 v[104:107], v[36:37], off offset:448
	global_load_dwordx4 v[168:171], v[38:39], off offset:448
	global_load_dwordx4 v[108:111], v[36:37], off offset:480
	global_load_dwordx4 v[172:175], v[38:39], off offset:480
	v_ashrrev_i32_e32 v36, 4, v40
	v_lshlrev_b32_e32 v37, 2, v41
	v_add_u32_e32 v24, s12, v36
	v_ashrrev_i32_e32 v25, 31, v24
	v_lshlrev_b64 v[26:27], 5, v[24:25]
	v_lshl_add_u64 v[26:27], s[6:7], 0, v[26:27]
	s_lshl_b32 s6, s8, 5
	v_lshl_or_b32 v20, v42, 2, s6
	s_movk_i32 s6, 0x84
	v_mul_lo_u32 v20, v20, s6
	v_add3_u32 v20, 0, v37, v20
	v_add_u32_e32 v21, 0x400, v20
	v_add_u32_e32 v22, 0x800, v20
	v_add_u32_e32 v23, 0xc00, v20
	s_waitcnt vmcnt(30)
	v_mfma_f32_32x32x16_bf16 v[0:15], v[48:51], v[112:115], 0
	s_waitcnt vmcnt(28)
	v_mfma_f32_32x32x16_bf16 v[0:15], v[52:55], v[116:119], v[0:15]
	s_waitcnt vmcnt(26)
	v_mfma_f32_32x32x16_bf16 v[0:15], v[56:59], v[120:123], v[0:15]
	s_waitcnt vmcnt(24)
	v_mfma_f32_32x32x16_bf16 v[0:15], v[60:63], v[124:127], v[0:15]
	s_waitcnt vmcnt(22)
	v_mfma_f32_32x32x16_bf16 v[0:15], v[64:67], v[128:131], v[0:15]
	s_waitcnt vmcnt(20)
	v_mfma_f32_32x32x16_bf16 v[0:15], v[68:71], v[132:135], v[0:15]
	s_waitcnt vmcnt(18)
	v_mfma_f32_32x32x16_bf16 v[0:15], v[72:75], v[136:139], v[0:15]
	s_waitcnt vmcnt(16)
	v_mfma_f32_32x32x16_bf16 v[0:15], v[76:79], v[140:143], v[0:15]
	s_waitcnt vmcnt(14)
	v_mfma_f32_32x32x16_bf16 v[0:15], v[80:83], v[144:147], v[0:15]
	s_waitcnt vmcnt(12)
	v_mfma_f32_32x32x16_bf16 v[0:15], v[84:87], v[148:151], v[0:15]
	s_waitcnt vmcnt(10)
	v_mfma_f32_32x32x16_bf16 v[0:15], v[88:91], v[152:155], v[0:15]
	s_waitcnt vmcnt(8)
	v_mfma_f32_32x32x16_bf16 v[0:15], v[92:95], v[156:159], v[0:15]
	s_waitcnt vmcnt(6)
	v_mfma_f32_32x32x16_bf16 v[0:15], v[96:99], v[160:163], v[0:15]
	s_waitcnt vmcnt(4)
	v_mfma_f32_32x32x16_bf16 v[0:15], v[100:103], v[164:167], v[0:15]
	s_waitcnt vmcnt(2)
	v_mfma_f32_32x32x16_bf16 v[0:15], v[104:107], v[168:171], v[0:15]
	s_waitcnt vmcnt(0)
	v_mfma_f32_32x32x16_bf16 v[0:15], v[108:111], v[172:175], v[0:15]
	s_nop 11
	ds_write2_b32 v20, v0, v1 offset1:33
	ds_write2_b32 v20, v2, v3 offset0:66 offset1:99
	ds_write2_b32 v21, v4, v5 offset0:8 offset1:41
	ds_write2_b32 v21, v6, v7 offset0:74 offset1:107
	ds_write2_b32 v22, v8, v9 offset0:16 offset1:49
	ds_write2_b32 v22, v10, v11 offset0:82 offset1:115
	ds_write2_b32 v23, v12, v13 offset0:24 offset1:57
	ds_write2_b32 v23, v14, v15 offset0:90 offset1:123
	s_waitcnt lgkmcnt(0)
	s_barrier
	global_load_dwordx4 v[0:3], v[26:27], off
	global_load_dwordx4 v[4:7], v[26:27], off offset:16
	v_lshlrev_b32_e32 v8, 2, v40
	v_and_b32_e32 v208, 60, v8
	global_load_dword v14, v208, s[2:3]
	v_mul_lo_u32 v12, v36, s6
	v_add3_u32 v12, 0, v208, v12
	ds_read_b32 v13, v12
	ds_read_b32 v15, v12 offset:4224
	ds_read_b32 v16, v12 offset:8448
	ds_read_b32 v17, v12 offset:12672
	ds_read_b32 v18, v12 offset:16896
	ds_read_b32 v19, v12 offset:21120
	ds_read_b32 v20, v12 offset:25344
	ds_read_b32 v21, v12 offset:29568
	s_waitcnt lgkmcnt(7)
	v_add_f32_e32 v12, 0, v13
	s_waitcnt lgkmcnt(6)
	v_add_f32_e32 v12, v12, v15
	s_waitcnt lgkmcnt(5)
	v_add_f32_e32 v12, v12, v16
	s_waitcnt lgkmcnt(4)
	v_add_f32_e32 v12, v12, v17
	s_waitcnt lgkmcnt(3)
	v_add_f32_e32 v15, v12, v18
	s_mov_b32 s2, 0xbfb8aa3b
	v_lshlrev_b64 v[8:9], 6, v[24:25]
	v_lshl_add_u64 v[10:11], s[82:83], 0, v[208:209]
	s_waitcnt vmcnt(2)
	v_mov_b32_e32 v12, v0
	s_waitcnt vmcnt(1)
	v_mov_b32_e32 v13, v4
	v_mov_b32_e32 v4, v1
	v_mov_b32_e32 v0, v2
	v_mov_b32_e32 v1, v6
	v_mov_b32_e32 v6, v3
	v_pk_add_f32 v[2:3], v[12:13], v[4:5]
	v_pk_add_f32 v[0:1], v[0:1], v[6:7]
	v_mov_b32_e32 v4, 0x41b17218
	v_pk_add_f32 v[0:1], v[2:3], v[0:1]
	s_nop 0
	v_add_f32_e32 v0, v0, v1
	v_mov_b32_e32 v1, 0x358637bd
	v_fmamk_f32 v0, v0, 0x3a000000, v1
	v_mul_f32_e32 v1, 0x4b800000, v0
	v_cmp_gt_f32_e32 vcc, s92, v0
	s_nop 1
	v_cndmask_b32_e32 v0, v0, v1, vcc
	v_rsq_f32_e32 v0, v0
	s_waitcnt lgkmcnt(2)
	v_add_f32_e32 v1, v15, v19
	s_waitcnt lgkmcnt(1)
	v_add_f32_e32 v1, v1, v20
	s_waitcnt lgkmcnt(0)
	v_add_f32_e32 v1, v1, v21
	v_mul_f32_e32 v2, 0x45800000, v0
	v_cndmask_b32_e32 v0, v0, v2, vcc
	s_waitcnt vmcnt(0)
	v_fmac_f32_e32 v14, v1, v0
	v_mul_f32_e64 v0, |v14|, s2
	v_exp_f32_e32 v2, v0
	v_lshl_add_u64 v[0:1], v[10:11], 0, v[8:9]
	v_add_co_u32_e32 v0, vcc, 0x8220000, v0
	v_add_f32_e32 v2, 1.0, v2
	v_cmp_gt_f32_e64 s[2:3], s92, v2
	v_addc_co_u32_e32 v1, vcc, 0, v1, vcc
	s_nop 0
	v_cndmask_b32_e64 v3, 0, 32, s[2:3]
	v_ldexp_f32 v2, v2, v3
	v_log_f32_e32 v2, v2
	v_cndmask_b32_e64 v4, 0, v4, s[2:3]
	s_mov_b32 s2, 0x7f800000
	v_min_f32_e32 v3, 0, v14
	v_mul_f32_e32 v5, 0x3f317217, v2
	v_cmp_lt_f32_e64 vcc, |v2|, s2
	s_mov_b32 s2, 0x3f317217
	v_fma_f32 v5, v2, s2, -v5
	v_fmac_f32_e32 v5, 0x3377d1cf, v2
	v_fmac_f32_e32 v5, 0x3f317217, v2
	v_cndmask_b32_e32 v2, v2, v5, vcc
	v_sub_f32_e32 v2, v2, v4
	v_sub_f32_e32 v2, v3, v2
	s_mov_b64 s[2:3], -1
	global_store_dword v[0:1], v2, off
	s_barrier
